# MLA attention steady-state tile loop hand-rewritten: 2x unrolled ping-pong score registers (no v_mov copies), exp-sum adds interleaved in MFMA gaps, static LDS offsets
# speedup vs baseline: 1.0383x; 1.0383x over previous
; #define LOADK(t) do { const int kp_ = TILE_KPOS(t); kreg = *(const u32x4*)((const char*)P.K + (size_t)(koff + (unsigned)(kp_ * KPITCH * 2))); if (VAR == 0 && tid < 256) pereg = *(const u32x4*)((const char*)P.KPE + (size_t)(peoff + (unsigned)(kp_ * 64))); } while (0)
; #define LOADV(t) do { const int kp_ = TILE_KPOS(t); vreg = *(const u32x4*)((const char*)P.VT + (size_t)(voff + (unsigned)(kp_ * 2))); } while (0)
; #define STOREK(buf) do { LAS unsigned char* kb_ = lds + (buf) * ABUF; *(LAS u32x4*)(kb_ + (tid >> 3) * KP + (tid & 7) * 16) = kreg; \
;         if (VAR == 0 && tid < 256) *(LAS u32x4*)(kb_ + (tid >> 2) * KP + 128 + (tid & 3) * 16) = pereg; } while (0)
; #define STOREV(buf) do { *(LAS u32x4*)(lds + (buf) * ABUF + KT_BYTES + (tid >> 3) * VP + (tid & 7) * 16) = vreg; } while (0)
; template <int VAR>
; __device__ __forceinline__ void attn_phase(LAS unsigned char* lds, const AttnP P, int vcu, int G, int wave_s) {
;     ...
;         LOADK(0); LOADV(0); STOREK(0); STOREV(0);
;         if (nt > 1) { LOADK(1); STOREK(1); }
;         __syncthreads();
;         f32x16 pc0, pc1; const f32x16 zero16 = {};
;         QK_TILE(pc0, pc1, 0, zero16);
;         float mref = rowmax32(pc0, pc1), lrun = 0.f;
;         if (VAR == 1) { const float sk = P.sink[hq] * LOG2E; mref = __builtin_fmaxf(mref, sk); lrun = (hi == 0) ? __builtin_amdgcn_exp2f(sk - mref) : 0.f; }
;         f32x16 negm = {};
;         if (USE_NEGM) {
; #pragma unroll
;             for (int r = 0; r < 16; ++r) { pc0[r] -= mref; pc1[r] -= mref; negm[r] = -mref; }
;         }
;         float rmc = 0.f;
;         bool need_c = true;
;         __syncthreads();
.LBB0_1173:
	s_or_b64 exec, exec, s[0:1]
	s_waitcnt vmcnt(0)
	ds_write_b128 v172, v[2:5] offset:22528
	s_and_saveexec_b64 s[0:1], s[2:3]
	ds_write_b128 v176, v[138:141] offset:22656
	s_or_b64 exec, exec, s[0:1]
	s_waitcnt lgkmcnt(0)
	s_barrier
	ds_read_b128 v[2:5], v174
	ds_read_b128 v[6:9], v174 offset:32
	s_waitcnt lgkmcnt(1)
	v_mfma_f32_32x32x16_bf16 v[34:49], v[2:5], v[114:117], 0
	ds_read_b128 v[2:5], v174 offset:6656
	ds_read_b128 v[10:13], v174 offset:6688
	v_readlane_b32 s36, v255, 18
	s_mov_b32 s0, s36
	v_readlane_b32 s37, v255, 19
	v_readlane_b32 s38, v255, 20
	v_readlane_b32 s39, v255, 21
	v_readlane_b32 s40, v255, 22
	s_waitcnt lgkmcnt(2)
	v_mfma_f32_32x32x16_bf16 v[34:49], v[6:9], v[118:121], v[34:49]
	v_readlane_b32 s41, v255, 23
	v_readlane_b32 s42, v255, 24
	v_readlane_b32 s43, v255, 25
	v_readlane_b32 s44, v255, 26
	v_readlane_b32 s45, v255, 27
	v_readlane_b32 s46, v255, 28
	v_readlane_b32 s47, v255, 29
	s_waitcnt lgkmcnt(1)
	v_mfma_f32_32x32x16_bf16 v[18:33], v[2:5], v[114:117], 0
	ds_read_b128 v[2:5], v174 offset:64
	ds_read_b128 v[6:9], v174 offset:96
	v_readlane_b32 s48, v255, 30
	v_readlane_b32 s49, v255, 31
	v_readlane_b32 s50, v255, 32
	v_readlane_b32 s51, v255, 33
	v_writelane_b32 v255, s0, 18
	s_mov_b32 s37, s36
	s_waitcnt lgkmcnt(1)
	v_mfma_f32_32x32x16_bf16 v[34:49], v[2:5], v[122:125], v[34:49]
	v_writelane_b32 v255, s1, 19
	v_writelane_b32 v255, s2, 20
	v_writelane_b32 v255, s3, 21
	v_writelane_b32 v255, s4, 22
	v_writelane_b32 v255, s5, 23
	v_writelane_b32 v255, s6, 24
	v_writelane_b32 v255, s7, 25
	v_mfma_f32_32x32x16_bf16 v[18:33], v[10:13], v[118:121], v[18:33]
	ds_read_b128 v[2:5], v174 offset:6720
	ds_read_b128 v[10:13], v174 offset:6752
	v_writelane_b32 v255, s8, 26
	v_writelane_b32 v255, s9, 27
	v_writelane_b32 v255, s10, 28
	v_writelane_b32 v255, s11, 29
	v_writelane_b32 v255, s12, 30
	v_writelane_b32 v255, s13, 31
	s_waitcnt lgkmcnt(2)
	v_mfma_f32_32x32x16_bf16 v[34:49], v[6:9], v[126:129], v[34:49]
	v_writelane_b32 v255, s14, 32
	s_mov_b32 s38, s36
	s_mov_b32 s39, s36
	s_mov_b32 s40, s36
	s_mov_b32 s41, s36
	s_mov_b32 s42, s36
	s_mov_b32 s43, s36
	s_waitcnt lgkmcnt(1)
	v_mfma_f32_32x32x16_bf16 v[18:33], v[2:5], v[122:125], v[18:33]
	ds_read_b128 v[2:5], v174 offset:128
	ds_read_b128 v[6:9], v174 offset:160
	ds_read_b128 v[50:53], v174 offset:6816
	s_mov_b32 s44, s36
	s_mov_b32 s45, s36
	s_mov_b32 s46, s36
	s_mov_b32 s47, s36
	s_mov_b32 s48, s36
	s_waitcnt lgkmcnt(2)
	v_mfma_f32_32x32x16_bf16 v[34:49], v[2:5], v[130:133], v[34:49]
	ds_read_b128 v[2:5], v174 offset:6784
	s_mov_b32 s49, s36
	s_mov_b32 s50, s36
	s_mov_b32 s51, s36
	v_writelane_b32 v255, s15, 33
	s_movk_i32 s0, 0x4200
	v_mul_lo_u32 v1, v1, s0
	v_mfma_f32_32x32x16_bf16 v[18:33], v[10:13], v[126:129], v[18:33]
	v_or_b32_e32 v1, v171, v1
	s_add_i32 s12, s9, -1
	v_lshl_add_u32 v181, s10, 7, v1
	v_mov_b32_e32 v1, 0
	s_mov_b32 s11, 1
	v_mov_b32_e32 v82, 0
	s_waitcnt lgkmcnt(0)
	v_mfma_f32_32x32x16_bf16 v[18:33], v[2:5], v[130:133], v[18:33]
	s_barrier
	v_mfma_f32_32x32x16_bf16 v[34:49], v[6:9], v[134:137], v[34:49]
	v_mov_b64_e32 v[2:3], s[36:37]
	v_mov_b64_e32 v[16:17], s[50:51]
	v_mov_b64_e32 v[4:5], s[38:39]
	v_mov_b64_e32 v[6:7], s[40:41]
	v_mov_b64_e32 v[8:9], s[42:43]
	v_mov_b64_e32 v[10:11], s[44:45]
	v_mov_b64_e32 v[12:13], s[46:47]
	v_mfma_f32_32x32x16_bf16 v[18:33], v[50:53], v[134:137], v[18:33]
	s_nop 3
	v_max_f32_e32 v54, v35, v35
	v_max_f32_e32 v55, v34, v34
	v_max_f32_e32 v54, v55, v54
	v_mov_b64_e32 v[14:15], s[48:49]
	s_nop 3
	v_max3_f32 v50, v36, v37, v19
	v_max3_f32 v51, v54, v18, v20
	v_max3_f32 v51, v51, v21, v38
	v_max3_f32 v50, v50, v40, v41
	v_max3_f32 v51, v51, v39, v22
	v_max3_f32 v50, v50, v24, v25
	v_max3_f32 v51, v51, v23, v42
	v_max3_f32 v50, v50, v44, v45
	v_max3_f32 v51, v51, v43, v26
	v_max3_f32 v50, v50, v28, v29
	v_max3_f32 v51, v51, v27, v46
	v_max3_f32 v50, v50, v48, v49
	v_max3_f32 v51, v51, v47, v30
	v_max3_f32 v50, v50, v32, v33
	v_max3_f32 v50, v51, v31, v50
	v_mov_b32_e32 v51, v50
	s_nop 1
	v_permlane32_swap_b32_e32 v50, v51
	v_max_f32_e32 v51, v51, v51
	v_max_f32_e32 v50, v50, v50
	v_max_f32_e32 v180, v50, v51
	v_xor_b32_e32 v66, 0x80000000, v180
	v_sub_f32_e32 v65, v33, v180
	v_sub_f32_e32 v64, v32, v180
	v_sub_f32_e32 v63, v31, v180
	v_sub_f32_e32 v62, v30, v180
	v_sub_f32_e32 v61, v29, v180
	v_sub_f32_e32 v60, v28, v180
	v_sub_f32_e32 v59, v27, v180
	v_sub_f32_e32 v58, v26, v180
	v_sub_f32_e32 v57, v25, v180
	v_sub_f32_e32 v56, v24, v180
	v_sub_f32_e32 v55, v23, v180
	v_sub_f32_e32 v54, v22, v180
	v_sub_f32_e32 v53, v21, v180
	v_sub_f32_e32 v52, v20, v180
	v_sub_f32_e32 v51, v19, v180
	v_sub_f32_e32 v50, v18, v180
	v_mov_b64_e32 v[32:33], v[16:17]
	v_sub_f32_e32 v49, v49, v180
	v_sub_f32_e32 v48, v48, v180
	v_sub_f32_e32 v47, v47, v180
	v_sub_f32_e32 v46, v46, v180
	v_sub_f32_e32 v45, v45, v180
	v_sub_f32_e32 v44, v44, v180
	v_sub_f32_e32 v43, v43, v180
	v_sub_f32_e32 v42, v42, v180
	v_sub_f32_e32 v41, v41, v180
	v_sub_f32_e32 v40, v40, v180
	v_sub_f32_e32 v39, v39, v180
	v_sub_f32_e32 v38, v38, v180
	v_sub_f32_e32 v37, v37, v180
	v_sub_f32_e32 v36, v36, v180
	v_sub_f32_e32 v35, v35, v180
	v_sub_f32_e32 v34, v34, v180
	v_mov_b64_e32 v[30:31], v[14:15]
	v_mov_b64_e32 v[28:29], v[12:13]
	v_mov_b64_e32 v[26:27], v[10:11]
	v_mov_b64_e32 v[24:25], v[8:9]
	v_mov_b64_e32 v[22:23], v[6:7]
	v_mov_b64_e32 v[20:21], v[4:5]
	v_mov_b64_e32 v[18:19], v[2:3]
	v_mov_b32_e32 v67, v66
	v_mov_b32_e32 v68, v66
	v_mov_b32_e32 v69, v66
	v_mov_b32_e32 v70, v66
	v_mov_b32_e32 v71, v66
	v_mov_b32_e32 v72, v66
	v_mov_b32_e32 v73, v66
	v_mov_b32_e32 v74, v66
	v_mov_b32_e32 v75, v66
	v_mov_b32_e32 v76, v66
	v_mov_b32_e32 v77, v66
	v_mov_b32_e32 v78, v66
	v_mov_b32_e32 v79, v66
	v_mov_b32_e32 v80, v66
	v_mov_b32_e32 v81, v66
	v_add_u32_e32 v228, v166, v165
	v_mov_b32_e32 v151, v82
; #define LOADK(t) do { const int kp_ = TILE_KPOS(t); kreg = *(const u32x4*)((const char*)P.K + (size_t)(koff + (unsigned)(kp_ * KPITCH * 2))); if (VAR == 0 && tid < 256) pereg = *(const u32x4*)((const char*)P.KPE + (size_t)(peoff + (unsigned)(kp_ * 64))); } while (0)
; #define LOADV(t) do { const int kp_ = TILE_KPOS(t); vreg = *(const u32x4*)((const char*)P.VT + (size_t)(voff + (unsigned)(kp_ * 2))); } while (0)
; template <int VAR>
; __device__ __forceinline__ void attn_phase(LAS unsigned char* lds, const AttnP P, int vcu, int G, int wave_s) {
;     ...
;         for (int t = 0; t < nt; ++t) {
;             const bool hn = (t + 1 < nt);
;             if (hn) { const int t2 = (t + 2 < nt) ? t + 2 : nt - 1; LOADK(t2); LOADV(t + 1); }
;             const bool need_n = hn && NEED(t + 1);
;             if (need_c && __any(rmc > THR)) {
.Lmla_A:
	s_add_i32 s13, s11, 1
	s_min_u32 s0, s13, s12
	s_add_i32 s0, s0, s10
	s_cmp_ge_i32 s0, s9
	s_cselect_b32 s1, s9, 0
	s_sub_i32 s19, s0, s1
	ds_read_b128 v[182:185], v174 offset:22528
	ds_read_b128 v[186:189], v174 offset:29184
	ds_read_b128 v[190:193], v174 offset:22560
	ds_read_b128 v[194:197], v174 offset:29216
	v_lshl_add_u32 v229, s19, 17, v178
	global_load_dwordx4 v[146:149], v229, s[52:53]
	s_and_saveexec_b64 s[0:1], s[2:3]
	s_cbranch_execz .Lmla_A_nope
	v_lshl_add_u32 v229, s19, 12, v179
	global_load_dwordx4 v[138:141], v229, s[62:63]
.Lmla_A_nope:
	s_or_b64 exec, exec, s[0:1]
	s_add_i32 s0, s10, s11
	s_cmp_ge_i32 s0, s9
	s_cselect_b32 s0, s9, 0
	s_lshl_b32 s0, s0, 7
	v_subrev_u32_e32 v229, s0, v181
	global_load_dwordx4 v[142:145], v229, s[56:57]
	v_cmp_lt_f32_e32 vcc, s66, v151
	s_cbranch_vccnz .Lmla_A_resc
; template <int VAR>
; __device__ __forceinline__ void attn_phase(LAS unsigned char* lds, const AttnP P, int vcu, int G, int wave_s) {
;     ...
;                 if (ND0 == 6) {
;                     KR1(0); KR1(1); KR1(2); KR1(3); SB();
;                     QK1(0, negm); EX2(pc0, 0, w0.x); KR1(4); SB();
;                     QK1(1, negm); EX2(pc0, 2, w0.y); KR1(5); SB();
;                     QK1(2, pn0); EX2(pc0, 4, w0.z); KR1(6); SB();
;                     QK1(3, pn1); EX2(pc0, 6, w0.w); KR1(7); SB();
;                     QK1(4, pn0); EX2(pc0, 8, w1.x); KR1(8); SB();
;                     QK1(5, pn1); EX2(pc0, 10, w1.y); KR1(9); SB();
;                     QK1(6, pn0); EX2(pc0, 12, w1.z); KR1(10); SB();
;                     QK1(7, pn1); EX2(pc0, 14, w1.w); KR1(11); SB();
;                     QK1(8, pn0); EX2(pc1, 0, w2.x); VR1(0); SB();
;                     QK1(9, pn1); EX2(pc1, 2, w2.y); VR1(1); SB();
;                     QK1(10, pn0); EX2(pc1, 4, w2.z); VR1(2); SB();
;                     QK1(11, pn1); EX2(pc1, 6, w2.w); VR1(3); SB();
;                 } else {
;                     KR1(0); KR1(1); KR1(2); KR1(3); SB();
;                     QK1(0, negm); EX2(pc0, 0, w0.x); EX2(pc0, 2, w0.y); KR1(4); SB();
;                     QK1(1, negm); EX2(pc0, 4, w0.z); EX2(pc0, 6, w0.w); KR1(5); SB();
;                     QK1(2, pn0); EX2(pc0, 8, w1.x); EX2(pc0, 10, w1.y); KR1(6); SB();
;                     QK1(3, pn1); EX2(pc0, 12, w1.z); EX2(pc0, 14, w1.w); KR1(7); SB();
;                     QK1(4, pn0); EX2(pc1, 0, w2.x); VR1(0); SB();
;                     QK1(5, pn1); EX2(pc1, 2, w2.y); VR1(1); SB();
;                     QK1(6, pn0); EX2(pc1, 4, w2.z); VR1(2); SB();
;                     QK1(7, pn1); EX2(pc1, 6, w2.w); VR1(3); SB();
;                 }
;                 PV1(0, w0); EX2(pc1, 8, w3.x); VR1(4); SB();
;                 PV1(1, w0); EX2(pc1, 10, w3.y); VR1(5); SB();
;                 PV1(2, w1); EX2(pc1, 12, w3.z); VR1(6); SB();
;                 PV1(3, w1); EX2(pc1, 14, w3.w); VR1(7); SB();
;                 lrun += sacc;
;                 PV1(4, w2); MASK_TILE(pn0, pn1, t + 1); SB();
;                 PV1(5, w2); SB();
;                 PV1(6, w3); SB();
;                 PV1(7, w3); rmn = rowmax32(pn0, pn1); if (!USE_NEGM) rmn -= mref; SB();
;     ...
;             if (hn) { STOREK(t & 1); STOREV((t + 1) & 1); }
;             __syncthreads();
.Lmla_A_go:
	v_exp_f32_e32 v222, v34
	v_exp_f32_e32 v223, v35
	v_add_f32_e32 v150, 0, v222
	v_cvt_pk_bf16_f32 v206, v222, v223
	v_add_f32_e32 v150, v223, v150
	v_exp_f32_e32 v224, v36
	v_exp_f32_e32 v225, v37
	v_add_f32_e32 v150, v224, v150
	v_cvt_pk_bf16_f32 v207, v224, v225
	v_add_f32_e32 v150, v225, v150
	s_waitcnt lgkmcnt(3)
	v_mfma_f32_32x32x16_bf16 v[82:97], v[182:185], v[114:117], v[66:81]
	ds_read_b128 v[198:201], v174 offset:22592
	v_exp_f32_e32 v222, v38
	v_exp_f32_e32 v223, v39
	v_add_f32_e32 v150, v222, v150
	v_cvt_pk_bf16_f32 v208, v222, v223
	v_add_f32_e32 v150, v223, v150
	s_waitcnt lgkmcnt(3)
	v_mfma_f32_32x32x16_bf16 v[98:113], v[186:189], v[114:117], v[66:81]
	ds_read_b128 v[202:205], v174 offset:29248
	v_exp_f32_e32 v224, v40
	v_exp_f32_e32 v225, v41
	v_add_f32_e32 v150, v224, v150
	v_cvt_pk_bf16_f32 v209, v224, v225
	v_add_f32_e32 v150, v225, v150
	s_waitcnt lgkmcnt(3)
	v_mfma_f32_32x32x16_bf16 v[82:97], v[190:193], v[118:121], v[82:97]
	ds_read_b128 v[182:185], v174 offset:22624
	v_exp_f32_e32 v222, v42
	v_exp_f32_e32 v223, v43
	v_add_f32_e32 v150, v222, v150
	v_cvt_pk_bf16_f32 v210, v222, v223
	v_add_f32_e32 v150, v223, v150
	s_waitcnt lgkmcnt(3)
	v_mfma_f32_32x32x16_bf16 v[98:113], v[194:197], v[118:121], v[98:113]
	ds_read_b128 v[186:189], v174 offset:29280
	v_exp_f32_e32 v224, v44
	v_exp_f32_e32 v225, v45
	v_add_f32_e32 v150, v224, v150
	v_cvt_pk_bf16_f32 v211, v224, v225
	v_add_f32_e32 v150, v225, v150
	s_waitcnt lgkmcnt(3)
	v_mfma_f32_32x32x16_bf16 v[82:97], v[198:201], v[122:125], v[82:97]
	ds_read_b128 v[190:193], v174 offset:22656
	v_exp_f32_e32 v222, v46
	v_exp_f32_e32 v223, v47
	v_add_f32_e32 v150, v222, v150
	v_cvt_pk_bf16_f32 v212, v222, v223
	v_add_f32_e32 v150, v223, v150
	s_waitcnt lgkmcnt(3)
	v_mfma_f32_32x32x16_bf16 v[98:113], v[202:205], v[122:125], v[98:113]
	ds_read_b128 v[194:197], v174 offset:29312
	v_exp_f32_e32 v224, v48
	v_exp_f32_e32 v225, v49
	v_add_f32_e32 v150, v224, v150
	v_cvt_pk_bf16_f32 v213, v224, v225
	v_add_f32_e32 v150, v225, v150
	s_waitcnt lgkmcnt(3)
	v_mfma_f32_32x32x16_bf16 v[82:97], v[182:185], v[126:129], v[82:97]
	ds_read_b128 v[198:201], v174 offset:22688
	v_exp_f32_e32 v222, v50
	v_exp_f32_e32 v223, v51
	v_add_f32_e32 v150, v222, v150
	v_cvt_pk_bf16_f32 v214, v222, v223
	v_add_f32_e32 v150, v223, v150
	s_waitcnt lgkmcnt(3)
	v_mfma_f32_32x32x16_bf16 v[98:113], v[186:189], v[126:129], v[98:113]
	ds_read_b128 v[202:205], v174 offset:29344
	v_exp_f32_e32 v224, v52
	v_exp_f32_e32 v225, v53
	v_add_f32_e32 v150, v224, v150
	v_cvt_pk_bf16_f32 v215, v224, v225
	v_add_f32_e32 v150, v225, v150
	s_waitcnt lgkmcnt(3)
	v_mfma_f32_32x32x16_bf16 v[82:97], v[190:193], v[130:133], v[82:97]
	ds_read_b128 v[182:185], v228 offset:13312
	v_exp_f32_e32 v222, v54
	v_exp_f32_e32 v223, v55
	v_add_f32_e32 v150, v222, v150
	v_cvt_pk_bf16_f32 v216, v222, v223
	v_add_f32_e32 v150, v223, v150
	s_waitcnt lgkmcnt(3)
	v_mfma_f32_32x32x16_bf16 v[98:113], v[194:197], v[130:133], v[98:113]
	ds_read_b128 v[186:189], v228 offset:17920
	v_exp_f32_e32 v224, v56
	v_exp_f32_e32 v225, v57
	v_add_f32_e32 v150, v224, v150
	v_cvt_pk_bf16_f32 v217, v224, v225
	v_add_f32_e32 v150, v225, v150
	s_waitcnt lgkmcnt(3)
	v_mfma_f32_32x32x16_bf16 v[82:97], v[198:201], v[134:137], v[82:97]
	ds_read_b128 v[190:193], v228 offset:13344
	v_exp_f32_e32 v222, v58
	v_exp_f32_e32 v223, v59
	v_add_f32_e32 v150, v222, v150
	v_cvt_pk_bf16_f32 v218, v222, v223
	v_add_f32_e32 v150, v223, v150
	s_waitcnt lgkmcnt(3)
	v_mfma_f32_32x32x16_bf16 v[98:113], v[202:205], v[134:137], v[98:113]
	ds_read_b128 v[194:197], v228 offset:17952
	v_exp_f32_e32 v224, v60
	v_exp_f32_e32 v225, v61
	v_add_f32_e32 v150, v224, v150
	v_cvt_pk_bf16_f32 v219, v224, v225
	v_add_f32_e32 v150, v225, v150
	s_waitcnt lgkmcnt(3)
	v_mfma_f32_32x32x16_bf16 v[2:17], v[182:185], v[206:209], v[2:17]
	ds_read_b128 v[198:201], v228 offset:13376
	v_exp_f32_e32 v222, v62
	v_exp_f32_e32 v223, v63
	v_add_f32_e32 v150, v222, v150
	v_cvt_pk_bf16_f32 v220, v222, v223
	v_add_f32_e32 v150, v223, v150
	s_waitcnt lgkmcnt(3)
	v_mfma_f32_32x32x16_bf16 v[18:33], v[186:189], v[206:209], v[18:33]
	ds_read_b128 v[202:205], v228 offset:17984
	v_exp_f32_e32 v224, v64
	v_exp_f32_e32 v225, v65
	v_add_f32_e32 v150, v224, v150
	v_cvt_pk_bf16_f32 v221, v224, v225
	v_add_f32_e32 v150, v225, v150
	s_waitcnt lgkmcnt(3)
	v_mfma_f32_32x32x16_bf16 v[2:17], v[190:193], v[210:213], v[2:17]
	ds_read_b128 v[182:185], v228 offset:13408
	v_max3_f32 v152, v82, v83, v84
	v_max3_f32 v153, v98, v99, v100
	v_max3_f32 v152, v152, v85, v86
	s_waitcnt lgkmcnt(3)
	v_mfma_f32_32x32x16_bf16 v[18:33], v[194:197], v[210:213], v[18:33]
	ds_read_b128 v[186:189], v228 offset:18016
	v_max3_f32 v153, v153, v101, v102
	v_max3_f32 v152, v152, v87, v88
	v_max3_f32 v153, v153, v103, v104
	s_waitcnt lgkmcnt(3)
	v_mfma_f32_32x32x16_bf16 v[2:17], v[198:201], v[214:217], v[2:17]
	v_max3_f32 v152, v152, v89, v90
	v_max3_f32 v153, v153, v105, v106
	v_max3_f32 v152, v152, v91, v92
	s_waitcnt lgkmcnt(2)
	v_mfma_f32_32x32x16_bf16 v[18:33], v[202:205], v[214:217], v[18:33]
	v_max3_f32 v153, v153, v107, v108
	v_max3_f32 v152, v152, v93, v94
	v_max3_f32 v153, v153, v109, v110
	s_waitcnt lgkmcnt(1)
	v_mfma_f32_32x32x16_bf16 v[2:17], v[182:185], v[218:221], v[2:17]
	v_max3_f32 v152, v152, v95, v96
	v_max3_f32 v153, v153, v111, v112
	s_waitcnt lgkmcnt(0)
	v_mfma_f32_32x32x16_bf16 v[18:33], v[186:189], v[218:221], v[18:33]
	v_max3_f32 v152, v152, v97, v113
	v_max_f32_e32 v152, v152, v153
	v_mov_b32_e32 v153, v152
	v_add_f32_e32 v1, v1, v150
	s_nop 0
	v_permlane32_swap_b32_e32 v152, v153
	s_waitcnt vmcnt(1)
	ds_write_b128 v172, v[146:149]
	s_and_saveexec_b64 s[0:1], s[2:3]
	ds_write_b128 v176, v[138:141] offset:128
	s_or_b64 exec, exec, s[0:1]
	v_max_f32_e32 v151, v152, v153
	v_add_u32_e32 v181, 0x80, v181
	s_add_i32 s11, s11, 1
	s_waitcnt vmcnt(0)
	ds_write_b128 v173, v[142:145] offset:35840
	s_cmp_eq_u32 s9, s11
	s_waitcnt lgkmcnt(0)
	s_barrier
	s_cbranch_scc1 .Lmla_exit_A
.Lmla_B:
	s_add_i32 s13, s11, 1
	s_min_u32 s0, s13, s12
	s_add_i32 s0, s0, s10
	s_cmp_ge_i32 s0, s9
	s_cselect_b32 s1, s9, 0
	s_sub_i32 s19, s0, s1
	ds_read_b128 v[182:185], v174
	ds_read_b128 v[186:189], v174 offset:6656
	ds_read_b128 v[190:193], v174 offset:32
	ds_read_b128 v[194:197], v174 offset:6688
	v_lshl_add_u32 v229, s19, 17, v178
	global_load_dwordx4 v[146:149], v229, s[52:53]
	s_and_saveexec_b64 s[0:1], s[2:3]
	s_cbranch_execz .Lmla_B_nope
	v_lshl_add_u32 v229, s19, 12, v179
	global_load_dwordx4 v[138:141], v229, s[62:63]

; template <int VAR>
; __device__ __forceinline__ void attn_phase(LAS unsigned char* lds, const AttnP P, int vcu, int G, int wave_s) {
;     ...
;                 if (ND0 == 6) {
;                     KR1(0); KR1(1); KR1(2); KR1(3); SB();
;                     QK1(0, negm); EX2(pc0, 0, w0.x); KR1(4); SB();
;                     QK1(1, negm); EX2(pc0, 2, w0.y); KR1(5); SB();
;                     QK1(2, pn0); EX2(pc0, 4, w0.z); KR1(6); SB();
;                     QK1(3, pn1); EX2(pc0, 6, w0.w); KR1(7); SB();
;                     QK1(4, pn0); EX2(pc0, 8, w1.x); KR1(8); SB();
;                     QK1(5, pn1); EX2(pc0, 10, w1.y); KR1(9); SB();
;                     QK1(6, pn0); EX2(pc0, 12, w1.z); KR1(10); SB();
;                     QK1(7, pn1); EX2(pc0, 14, w1.w); KR1(11); SB();
;                     QK1(8, pn0); EX2(pc1, 0, w2.x); VR1(0); SB();
;                     QK1(9, pn1); EX2(pc1, 2, w2.y); VR1(1); SB();
;                     QK1(10, pn0); EX2(pc1, 4, w2.z); VR1(2); SB();
;                     QK1(11, pn1); EX2(pc1, 6, w2.w); VR1(3); SB();
;                 } else {
;                     KR1(0); KR1(1); KR1(2); KR1(3); SB();
;                     QK1(0, negm); EX2(pc0, 0, w0.x); EX2(pc0, 2, w0.y); KR1(4); SB();
;                     QK1(1, negm); EX2(pc0, 4, w0.z); EX2(pc0, 6, w0.w); KR1(5); SB();
;                     QK1(2, pn0); EX2(pc0, 8, w1.x); EX2(pc0, 10, w1.y); KR1(6); SB();
;                     QK1(3, pn1); EX2(pc0, 12, w1.z); EX2(pc0, 14, w1.w); KR1(7); SB();
;                     QK1(4, pn0); EX2(pc1, 0, w2.x); VR1(0); SB();
;                     QK1(5, pn1); EX2(pc1, 2, w2.y); VR1(1); SB();
;                     QK1(6, pn0); EX2(pc1, 4, w2.z); VR1(2); SB();
;                     QK1(7, pn1); EX2(pc1, 6, w2.w); VR1(3); SB();
;                 }
;                 PV1(0, w0); EX2(pc1, 8, w3.x); VR1(4); SB();
;                 PV1(1, w0); EX2(pc1, 10, w3.y); VR1(5); SB();
;                 PV1(2, w1); EX2(pc1, 12, w3.z); VR1(6); SB();
;                 PV1(3, w1); EX2(pc1, 14, w3.w); VR1(7); SB();
;                 lrun += sacc;
;                 PV1(4, w2); MASK_TILE(pn0, pn1, t + 1); SB();
;                 PV1(5, w2); SB();
;                 PV1(6, w3); SB();
;                 PV1(7, w3); rmn = rowmax32(pn0, pn1); if (!USE_NEGM) rmn -= mref; SB();
;     ...
;             if (hn) { STOREK(t & 1); STOREV((t + 1) & 1); }
;             __syncthreads();
.Lmla_B_go:
	v_exp_f32_e32 v222, v82
	v_exp_f32_e32 v223, v83
	v_add_f32_e32 v150, 0, v222
	v_cvt_pk_bf16_f32 v206, v222, v223
	v_add_f32_e32 v150, v223, v150
	v_exp_f32_e32 v224, v84
	v_exp_f32_e32 v225, v85
	v_add_f32_e32 v150, v224, v150
	v_cvt_pk_bf16_f32 v207, v224, v225
	v_add_f32_e32 v150, v225, v150
	s_waitcnt lgkmcnt(3)
	v_mfma_f32_32x32x16_bf16 v[34:49], v[182:185], v[114:117], v[66:81]
	ds_read_b128 v[198:201], v174 offset:64
	v_exp_f32_e32 v222, v86
	v_exp_f32_e32 v223, v87
	v_add_f32_e32 v150, v222, v150
	v_cvt_pk_bf16_f32 v208, v222, v223
	v_add_f32_e32 v150, v223, v150
	s_waitcnt lgkmcnt(3)
	v_mfma_f32_32x32x16_bf16 v[50:65], v[186:189], v[114:117], v[66:81]
	ds_read_b128 v[202:205], v174 offset:6720
	v_exp_f32_e32 v224, v88
	v_exp_f32_e32 v225, v89
	v_add_f32_e32 v150, v224, v150
	v_cvt_pk_bf16_f32 v209, v224, v225
	v_add_f32_e32 v150, v225, v150
	s_waitcnt lgkmcnt(3)
	v_mfma_f32_32x32x16_bf16 v[34:49], v[190:193], v[118:121], v[34:49]
	ds_read_b128 v[182:185], v174 offset:96
	v_exp_f32_e32 v222, v90
	v_exp_f32_e32 v223, v91
	v_add_f32_e32 v150, v222, v150
	v_cvt_pk_bf16_f32 v210, v222, v223
	v_add_f32_e32 v150, v223, v150
	s_waitcnt lgkmcnt(3)
	v_mfma_f32_32x32x16_bf16 v[50:65], v[194:197], v[118:121], v[50:65]
	ds_read_b128 v[186:189], v174 offset:6752
	v_exp_f32_e32 v224, v92
	v_exp_f32_e32 v225, v93
	v_add_f32_e32 v150, v224, v150
	v_cvt_pk_bf16_f32 v211, v224, v225
	v_add_f32_e32 v150, v225, v150
	s_waitcnt lgkmcnt(3)
	v_mfma_f32_32x32x16_bf16 v[34:49], v[198:201], v[122:125], v[34:49]
	ds_read_b128 v[190:193], v174 offset:128
	v_exp_f32_e32 v222, v94
	v_exp_f32_e32 v223, v95
	v_add_f32_e32 v150, v222, v150
	v_cvt_pk_bf16_f32 v212, v222, v223
	v_add_f32_e32 v150, v223, v150
	s_waitcnt lgkmcnt(3)
	v_mfma_f32_32x32x16_bf16 v[50:65], v[202:205], v[122:125], v[50:65]
	ds_read_b128 v[194:197], v174 offset:6784
	v_exp_f32_e32 v224, v96
	v_exp_f32_e32 v225, v97
	v_add_f32_e32 v150, v224, v150
	v_cvt_pk_bf16_f32 v213, v224, v225
	v_add_f32_e32 v150, v225, v150
	s_waitcnt lgkmcnt(3)
	v_mfma_f32_32x32x16_bf16 v[34:49], v[182:185], v[126:129], v[34:49]
	ds_read_b128 v[198:201], v174 offset:160
	v_exp_f32_e32 v222, v98
	v_exp_f32_e32 v223, v99
	v_add_f32_e32 v150, v222, v150
	v_cvt_pk_bf16_f32 v214, v222, v223
	v_add_f32_e32 v150, v223, v150
	s_waitcnt lgkmcnt(3)
	v_mfma_f32_32x32x16_bf16 v[50:65], v[186:189], v[126:129], v[50:65]
	ds_read_b128 v[202:205], v174 offset:6816
	v_exp_f32_e32 v224, v100
	v_exp_f32_e32 v225, v101
	v_add_f32_e32 v150, v224, v150
	v_cvt_pk_bf16_f32 v215, v224, v225
	v_add_f32_e32 v150, v225, v150
	s_waitcnt lgkmcnt(3)
	v_mfma_f32_32x32x16_bf16 v[34:49], v[190:193], v[130:133], v[34:49]
	ds_read_b128 v[182:185], v228 offset:35840
	v_exp_f32_e32 v222, v102
	v_exp_f32_e32 v223, v103
	v_add_f32_e32 v150, v222, v150
	v_cvt_pk_bf16_f32 v216, v222, v223
	v_add_f32_e32 v150, v223, v150
	s_waitcnt lgkmcnt(3)
	v_mfma_f32_32x32x16_bf16 v[50:65], v[194:197], v[130:133], v[50:65]
	ds_read_b128 v[186:189], v228 offset:40448
	v_exp_f32_e32 v224, v104
	v_exp_f32_e32 v225, v105
	v_add_f32_e32 v150, v224, v150
	v_cvt_pk_bf16_f32 v217, v224, v225
	v_add_f32_e32 v150, v225, v150
	s_waitcnt lgkmcnt(3)
	v_mfma_f32_32x32x16_bf16 v[34:49], v[198:201], v[134:137], v[34:49]
	ds_read_b128 v[190:193], v228 offset:35872
	v_exp_f32_e32 v222, v106
	v_exp_f32_e32 v223, v107
	v_add_f32_e32 v150, v222, v150
	v_cvt_pk_bf16_f32 v218, v222, v223
	v_add_f32_e32 v150, v223, v150
	s_waitcnt lgkmcnt(3)
	v_mfma_f32_32x32x16_bf16 v[50:65], v[202:205], v[134:137], v[50:65]
	ds_read_b128 v[194:197], v228 offset:40480
	v_exp_f32_e32 v224, v108
	v_exp_f32_e32 v225, v109
	v_add_f32_e32 v150, v224, v150
	v_cvt_pk_bf16_f32 v219, v224, v225
	v_add_f32_e32 v150, v225, v150
	s_waitcnt lgkmcnt(3)
	v_mfma_f32_32x32x16_bf16 v[2:17], v[182:185], v[206:209], v[2:17]
	ds_read_b128 v[198:201], v228 offset:35904
	v_exp_f32_e32 v222, v110
	v_exp_f32_e32 v223, v111
	v_add_f32_e32 v150, v222, v150
	v_cvt_pk_bf16_f32 v220, v222, v223
	v_add_f32_e32 v150, v223, v150
	s_waitcnt lgkmcnt(3)
	v_mfma_f32_32x32x16_bf16 v[18:33], v[186:189], v[206:209], v[18:33]
	ds_read_b128 v[202:205], v228 offset:40512
	v_exp_f32_e32 v224, v112
	v_exp_f32_e32 v225, v113
	v_add_f32_e32 v150, v224, v150
	v_cvt_pk_bf16_f32 v221, v224, v225
	v_add_f32_e32 v150, v225, v150
	s_waitcnt lgkmcnt(3)
	v_mfma_f32_32x32x16_bf16 v[2:17], v[190:193], v[210:213], v[2:17]
	ds_read_b128 v[182:185], v228 offset:35936
	v_max3_f32 v152, v34, v35, v36
	v_max3_f32 v153, v50, v51, v52
	v_max3_f32 v152, v152, v37, v38
	s_waitcnt lgkmcnt(3)
	v_mfma_f32_32x32x16_bf16 v[18:33], v[194:197], v[210:213], v[18:33]
	ds_read_b128 v[186:189], v228 offset:40544
	v_max3_f32 v153, v153, v53, v54
	v_max3_f32 v152, v152, v39, v40
	v_max3_f32 v153, v153, v55, v56
	s_waitcnt lgkmcnt(3)
	v_mfma_f32_32x32x16_bf16 v[2:17], v[198:201], v[214:217], v[2:17]
	v_max3_f32 v152, v152, v41, v42
	v_max3_f32 v153, v153, v57, v58
	v_max3_f32 v152, v152, v43, v44
	s_waitcnt lgkmcnt(2)
	v_mfma_f32_32x32x16_bf16 v[18:33], v[202:205], v[214:217], v[18:33]
	v_max3_f32 v153, v153, v59, v60
	v_max3_f32 v152, v152, v45, v46
	v_max3_f32 v153, v153, v61, v62
	s_waitcnt lgkmcnt(1)
	v_mfma_f32_32x32x16_bf16 v[2:17], v[182:185], v[218:221], v[2:17]
	v_max3_f32 v152, v152, v47, v48
	v_max3_f32 v153, v153, v63, v64
	s_waitcnt lgkmcnt(0)
	v_mfma_f32_32x32x16_bf16 v[18:33], v[186:189], v[218:221], v[18:33]
	v_max3_f32 v152, v152, v49, v65
	v_max_f32_e32 v152, v152, v153
	v_mov_b32_e32 v153, v152
	v_add_f32_e32 v1, v1, v150
	s_nop 0
	v_permlane32_swap_b32_e32 v152, v153
	s_waitcnt vmcnt(1)
	ds_write_b128 v172, v[146:149] offset:22528
	s_and_saveexec_b64 s[0:1], s[2:3]
	ds_write_b128 v176, v[138:141] offset:22656
	s_or_b64 exec, exec, s[0:1]
	v_max_f32_e32 v151, v152, v153
	v_add_u32_e32 v181, 0x80, v181
	s_add_i32 s11, s11, 1
	s_waitcnt vmcnt(0)
	ds_write_b128 v173, v[142:145] offset:13312
	s_cmp_eq_u32 s9, s11
	s_waitcnt lgkmcnt(0)
	s_barrier
	s_cbranch_scc1 .Lmla_exit_B
	s_branch .Lmla_A
; template <int VAR>
; __device__ __forceinline__ void attn_phase(LAS unsigned char* lds, const AttnP P, int vcu, int G, int wave_s) {
;     ...
;             if (need_c && __any(rmc > THR)) {
;                 const float dl = __builtin_fmaxf(rmc, 0.f), f = __builtin_amdgcn_exp2f(-dl);
;                 mref += dl; lrun *= f;
; #pragma unroll
;                 for (int r = 0; r < 16; ++r) { if (USE_NEGM) { pc0[r] -= dl; pc1[r] -= dl; negm[r] = -mref; } o0[r] *= f; o1[r] *= f; }
;             }
;     ...
;             pc0 = pn0; pc1 = pn1; rmc = rmn; need_c = need_n;
.Lmla_exit_A:
	v_mov_b64_e32 v[34:35], v[82:83]
	v_mov_b64_e32 v[36:37], v[84:85]
	v_mov_b64_e32 v[38:39], v[86:87]
	v_mov_b64_e32 v[40:41], v[88:89]
	v_mov_b64_e32 v[42:43], v[90:91]
	v_mov_b64_e32 v[44:45], v[92:93]
	v_mov_b64_e32 v[46:47], v[94:95]
	v_mov_b64_e32 v[48:49], v[96:97]
	v_mov_b64_e32 v[50:51], v[98:99]
	v_mov_b64_e32 v[52:53], v[100:101]
	v_mov_b64_e32 v[54:55], v[102:103]
	v_mov_b64_e32 v[56:57], v[104:105]
	v_mov_b64_e32 v[58:59], v[106:107]
	v_mov_b64_e32 v[60:61], v[108:109]
	v_mov_b64_e32 v[62:63], v[110:111]
	v_mov_b64_e32 v[64:65], v[112:113]
	v_mov_b32_e32 v82, v151
	s_mov_b32 s11, 0x5800
	s_branch .LBB0_1185
.Lmla_exit_B:
	v_mov_b32_e32 v82, v151
	s_mov_b32 s11, 0
	s_branch .LBB0_1185
.Lmla_A_resc:
	v_max_f32_e32 v152, v151, v151
	v_max_f32_e32 v152, 0, v152
	v_exp_f32_e64 v153, -v152
	v_add_f32_e32 v180, v180, v152
	v_sub_f32_e32 v34, v34, v152
	v_sub_f32_e32 v35, v35, v152
	v_sub_f32_e32 v36, v36, v152
	v_sub_f32_e32 v37, v37, v152
	v_sub_f32_e32 v38, v38, v152
	v_sub_f32_e32 v39, v39, v152
	v_sub_f32_e32 v40, v40, v152
	v_sub_f32_e32 v41, v41, v152
	v_sub_f32_e32 v42, v42, v152
	v_sub_f32_e32 v43, v43, v152
	v_sub_f32_e32 v44, v44, v152
	v_sub_f32_e32 v45, v45, v152
	v_sub_f32_e32 v46, v46, v152
	v_sub_f32_e32 v47, v47, v152
	v_sub_f32_e32 v48, v48, v152
	v_sub_f32_e32 v49, v49, v152
	v_sub_f32_e32 v50, v50, v152
	v_sub_f32_e32 v51, v51, v152
	v_sub_f32_e32 v52, v52, v152
	v_sub_f32_e32 v53, v53, v152
	v_sub_f32_e32 v54, v54, v152
	v_sub_f32_e32 v55, v55, v152
	v_sub_f32_e32 v56, v56, v152
	v_sub_f32_e32 v57, v57, v152
	v_sub_f32_e32 v58, v58, v152
	v_sub_f32_e32 v59, v59, v152
	v_sub_f32_e32 v60, v60, v152
	v_sub_f32_e32 v61, v61, v152
	v_sub_f32_e32 v62, v62, v152
	v_sub_f32_e32 v63, v63, v152
	v_sub_f32_e32 v64, v64, v152
	v_sub_f32_e32 v65, v65, v152
	v_mul_f32_e32 v2, v2, v153
	v_mul_f32_e32 v3, v3, v153
	v_mul_f32_e32 v4, v4, v153
	v_mul_f32_e32 v5, v5, v153
	v_mul_f32_e32 v6, v6, v153
	v_mul_f32_e32 v7, v7, v153
	v_mul_f32_e32 v8, v8, v153
	v_mul_f32_e32 v9, v9, v153
	v_mul_f32_e32 v10, v10, v153
	v_mul_f32_e32 v11, v11, v153
	v_mul_f32_e32 v12, v12, v153
	v_mul_f32_e32 v13, v13, v153
	v_mul_f32_e32 v14, v14, v153
	v_mul_f32_e32 v15, v15, v153
	v_mul_f32_e32 v16, v16, v153
	v_mul_f32_e32 v17, v17, v153
	v_mul_f32_e32 v18, v18, v153
	v_mul_f32_e32 v19, v19, v153
	v_mul_f32_e32 v20, v20, v153
	v_mul_f32_e32 v21, v21, v153
	v_mul_f32_e32 v22, v22, v153
	v_mul_f32_e32 v23, v23, v153
	v_mul_f32_e32 v24, v24, v153
	v_mul_f32_e32 v25, v25, v153
	v_mul_f32_e32 v26, v26, v153
	v_mul_f32_e32 v27, v27, v153
	v_mul_f32_e32 v28, v28, v153
	v_mul_f32_e32 v29, v29, v153
	v_mul_f32_e32 v30, v30, v153
	v_mul_f32_e32 v31, v31, v153
	v_mul_f32_e32 v32, v32, v153
	v_mul_f32_e32 v33, v33, v153
	v_mul_f32_e32 v1, v1, v153
	v_xor_b32_e32 v66, 0x80000000, v180
	v_mov_b32_e32 v67, v66
	v_mov_b32_e32 v68, v66
	v_mov_b32_e32 v69, v66
	v_mov_b32_e32 v70, v66
	v_mov_b32_e32 v71, v66
	v_mov_b32_e32 v72, v66
	v_mov_b32_e32 v73, v66
	v_mov_b32_e32 v74, v66
	v_mov_b32_e32 v75, v66
	v_mov_b32_e32 v76, v66
	v_mov_b32_e32 v77, v66
	v_mov_b32_e32 v78, v66
	v_mov_b32_e32 v79, v66
	v_mov_b32_e32 v80, v66
	v_mov_b32_e32 v81, v66
	s_branch .Lmla_A_go
.Lmla_B_resc:
	v_max_f32_e32 v152, v151, v151
	v_max_f32_e32 v152, 0, v152
	v_exp_f32_e64 v153, -v152
	v_add_f32_e32 v180, v180, v152
	v_sub_f32_e32 v82, v82, v152
	v_sub_f32_e32 v83, v83, v152
	v_sub_f32_e32 v84, v84, v152
	v_sub_f32_e32 v85, v85, v152
	v_sub_f32_e32 v86, v86, v152
	v_sub_f32_e32 v87, v87, v152
	v_sub_f32_e32 v88, v88, v152
	v_sub_f32_e32 v89, v89, v152
	v_sub_f32_e32 v90, v90, v152
	v_sub_f32_e32 v91, v91, v152
	v_sub_f32_e32 v92, v92, v152
	v_sub_f32_e32 v93, v93, v152
	v_sub_f32_e32 v94, v94, v152
	v_sub_f32_e32 v95, v95, v152
	v_sub_f32_e32 v96, v96, v152
	v_sub_f32_e32 v97, v97, v152
	v_sub_f32_e32 v98, v98, v152
	v_sub_f32_e32 v99, v99, v152
	v_sub_f32_e32 v100, v100, v152
	v_sub_f32_e32 v101, v101, v152
	v_sub_f32_e32 v102, v102, v152
	v_sub_f32_e32 v103, v103, v152
	v_sub_f32_e32 v104, v104, v152
	v_sub_f32_e32 v105, v105, v152
	v_sub_f32_e32 v106, v106, v152
	v_sub_f32_e32 v107, v107, v152
	v_sub_f32_e32 v108, v108, v152
	v_sub_f32_e32 v109, v109, v152
	v_sub_f32_e32 v110, v110, v152
	v_sub_f32_e32 v111, v111, v152
	v_sub_f32_e32 v112, v112, v152
	v_sub_f32_e32 v113, v113, v152
	v_mul_f32_e32 v2, v2, v153
	v_mul_f32_e32 v3, v3, v153
	v_mul_f32_e32 v4, v4, v153
	v_mul_f32_e32 v5, v5, v153
	v_mul_f32_e32 v6, v6, v153
	v_mul_f32_e32 v7, v7, v153
	v_mul_f32_e32 v8, v8, v153
	v_mul_f32_e32 v9, v9, v153
	v_mul_f32_e32 v10, v10, v153
	v_mul_f32_e32 v11, v11, v153
	v_mul_f32_e32 v12, v12, v153
	v_mul_f32_e32 v13, v13, v153
	v_mul_f32_e32 v14, v14, v153
	v_mul_f32_e32 v15, v15, v153
	v_mul_f32_e32 v16, v16, v153
	v_mul_f32_e32 v17, v17, v153
	v_mul_f32_e32 v18, v18, v153
	v_mul_f32_e32 v19, v19, v153
	v_mul_f32_e32 v20, v20, v153
	v_mul_f32_e32 v21, v21, v153
	v_mul_f32_e32 v22, v22, v153
	v_mul_f32_e32 v23, v23, v153
	v_mul_f32_e32 v24, v24, v153
	v_mul_f32_e32 v25, v25, v153
	v_mul_f32_e32 v26, v26, v153
	v_mul_f32_e32 v27, v27, v153
	v_mul_f32_e32 v28, v28, v153
	v_mul_f32_e32 v29, v29, v153
	v_mul_f32_e32 v30, v30, v153
	v_mul_f32_e32 v31, v31, v153
	v_mul_f32_e32 v32, v32, v153
	v_mul_f32_e32 v33, v33, v153
	v_mul_f32_e32 v1, v1, v153
	v_xor_b32_e32 v66, 0x80000000, v180
	v_mov_b32_e32 v67, v66
	v_mov_b32_e32 v68, v66
	v_mov_b32_e32 v69, v66
	v_mov_b32_e32 v70, v66
	v_mov_b32_e32 v71, v66
	v_mov_b32_e32 v72, v66
	v_mov_b32_e32 v73, v66
	v_mov_b32_e32 v74, v66
	v_mov_b32_e32 v75, v66
	v_mov_b32_e32 v76, v66
	v_mov_b32_e32 v77, v66
	v_mov_b32_e32 v78, v66
	v_mov_b32_e32 v79, v66
	v_mov_b32_e32 v80, v66
	v_mov_b32_e32 v81, v66
	s_branch .Lmla_B_go
